# FoX loop: 60 packed f32 VOP3P ops (v_pk_fma/add/mul_f32) split into scalar v_fma/v_add/v_mul pairs (same arithmetic, bit-identical)
# speedup vs baseline: 1.0062x; 1.0015x over previous
; DI void fox_attn(const Params& P, int bh, int qb, unsigned char* smem, int tt) {
;     ...
;         {
;             const float sh = cq - m;
;             const f32x2v sh2 = {sh, sh};
;             f32x2v rs2 = {0.f, 0.f};
; #pragma unroll
;             for (int mt = 0; mt < 2; ++mt)
; #pragma unroll
;                 for (int p2 = 0; p2 < 8; ++p2) {
;                     const f32x2v sv = {sacc[mt][2 * p2], sacc[mt][2 * p2 + 1]};
;                     const f32x2v t = sv + sh2;
;                     f32x2v pp; pp.x = __builtin_amdgcn_exp2f(t.x); pp.y = __builtin_amdgcn_exp2f(t.y);
;                     sacc[mt][2 * p2] = pp.x; sacc[mt][2 * p2 + 1] = pp.y;
;                     rs2 = rs2 + pp;
;                 }
;             l += rs2.x + rs2.y;
;         }
.LBB0_545:
	s_or_b64 exec, exec, s[36:37]
	v_add_f32_e32 v44, 0, v44
	v_add_f32_e32 v45, 0, v45
	s_add_i32 s34, s34, 64
	v_add_f32_e32 v44, v46, v44
	v_add_f32_e32 v45, v47, v45
	v_cmp_eq_u32_e32 vcc, s47, v123
	v_add_f32_e32 v44, v48, v44
	v_add_f32_e32 v45, v49, v45
	v_subrev_u32_e32 v127, 64, v127
	v_add_f32_e32 v44, v50, v44
	v_add_f32_e32 v45, v51, v45
	s_or_b64 s[30:31], vcc, s[30:31]
	v_add_f32_e32 v44, v54, v44
	v_add_f32_e32 v45, v55, v45
	v_lshl_add_u64 v[108:109], v[108:109], 0, s[18:19]
	v_add_f32_e32 v44, v58, v44
	v_add_f32_e32 v45, v59, v45
	s_waitcnt lgkmcnt(0)
	v_add_f32_e32 v44, v64, v44
	v_add_f32_e32 v45, v65, v45
	s_barrier
	v_add_f32_e32 v44, v56, v44
	v_add_f32_e32 v45, v57, v45
	s_nop 0
	v_add_f32_e32 v44, v62, v44
	v_add_f32_e32 v45, v63, v45
	s_nop 0
	v_add_f32_e32 v44, v52, v44
	v_add_f32_e32 v45, v53, v45
	s_nop 0
	v_add_f32_e32 v44, v60, v44
	v_add_f32_e32 v45, v61, v45
	s_nop 0
	v_add_f32_e32 v38, v38, v44
	v_add_f32_e32 v39, v39, v45
	s_nop 0
	v_add_f32_e32 v38, v42, v38
	v_add_f32_e32 v39, v43, v39
	s_nop 0
	v_add_f32_e32 v36, v36, v38
	v_add_f32_e32 v37, v37, v39
	s_nop 0
	v_add_f32_e32 v36, v40, v36
	v_add_f32_e32 v37, v41, v37
	s_nop 0
	v_add_f32_e32 v34, v34, v36
	v_add_f32_e32 v35, v35, v37
	s_nop 0
	v_add_f32_e32 v0, v34, v35
	v_add_f32_e32 v120, v120, v0
	s_andn2_b64 exec, exec, s[30:31]
	s_cbranch_execz .LBB0_557

; #define MFMA32(a, b, c) __builtin_amdgcn_mfma_f32_32x32x16_bf16((a), (b), (c), 0, 0, 0)
; DI void fox_attn(const Params& P, int bh, int qb, unsigned char* smem, int tt) {
;     ...
;         f32x16 sacc[2];
;         f32x4 ckv[2][4];
;         {
;             bf16x8 kf[2][4];
; #pragma unroll
;             for (int mt = 0; mt < 2; ++mt)
; #pragma unroll
;                 for (int ks = 0; ks < 4; ++ks) kf[mt][ks] = *(const bf16x8*)(Ks + (mt * 32 + r) * 72 + ks * 16 + h2 * 8);
; #pragma unroll
;             for (int mt = 0; mt < 2; ++mt)
; #pragma unroll
;                 for (int g = 0; g < 4; ++g) ckv[mt][g] = *(const f32x4*)(cks + mt * 32 + 8 * g + 4 * h2);
; #pragma unroll
;             for (int e = 0; e < 16; ++e) { sacc[0][e] = 0.f; sacc[1][e] = 0.f; }
;             __builtin_amdgcn_sched_barrier(0);
; #pragma unroll
;             for (int ks = 0; ks < 4; ++ks) { sacc[0] = MFMA32(kf[0][ks], Qf[ks], sacc[0]); sacc[1] = MFMA32(kf[1][ks], Qf[ks], sacc[1]); }
;         }
;         const bool diag = kt >= ntiles - 2;
;         float mx = -1e30f;
;         {
;             const f32x2v csc = {0.125f * L2E, 0.125f * L2E};
; #pragma unroll
;             for (int mt = 0; mt < 2; ++mt)
; #pragma unroll
;                 for (int g = 0; g < 4; ++g) {
;                     const f32x4 ck4 = ckv[mt][g];
;                     const f32x2v c01 = {ck4[0], ck4[1]}, c23 = {ck4[2], ck4[3]};
;                     const f32x2v a01 = {sacc[mt][4 * g], sacc[mt][4 * g + 1]}, a23 = {sacc[mt][4 * g + 2], sacc[mt][4 * g + 3]};
;                     const f32x2v s01 = a01 * csc - c01, s23 = a23 * csc - c23;
;                     sacc[mt][4 * g] = s01.x; sacc[mt][4 * g + 1] = s01.y; sacc[mt][4 * g + 2] = s23.x; sacc[mt][4 * g + 3] = s23.y;
;                     mx = fmaxf(fmaxf(mx, s01.x), s01.y); mx = fmaxf(fmaxf(mx, s23.x), s23.y);
;                 }
;         }
;         if (diag) {
;             mx = -1e30f;
;             const int qrel = q - kt * 64 - 4 * h2;
; #pragma unroll
;             for (int mt = 0; mt < 2; ++mt)
; #pragma unroll
;                 for (int e = 0; e < 16; ++e) {
;                     const int krel = mt * 32 + (e & 3) + 8 * (e >> 2);
;                     const float sv = (krel > qrel) ? -1e30f : sacc[mt][e];
;                     sacc[mt][e] = sv;
;                     mx = fmaxf(mx, sv);
;                 }
;         }
.LBB0_550:
	s_or_b64 exec, exec, s[36:37]
	s_bitcmp1_b32 s56, 0
	s_cselect_b32 s35, 0x4900, 0
	v_add_u32_e32 v0, s35, v125
	v_lshl_add_u32 v42, v124, 1, v0
	ds_read_b128 v[34:37], v42
	ds_read_b128 v[110:113], v42 offset:32
	ds_read_b128 v[114:117], v42 offset:64
	ds_read_b128 v[132:135], v42 offset:96
	ds_read_b128 v[38:41], v42 offset:4608
	ds_read_b128 v[136:139], v42 offset:4640
	ds_read_b128 v[140:143], v42 offset:4672
	ds_read_b128 v[144:147], v42 offset:4704
	ds_read_b128 v[148:151], v0 offset:18432
	ds_read_b128 v[152:155], v0 offset:18464
	ds_read_b128 v[156:159], v0 offset:18496
	ds_read_b128 v[160:163], v0 offset:18528
	ds_read_b128 v[170:173], v0 offset:18560
	ds_read_b128 v[174:177], v0 offset:18592
	ds_read_b128 v[178:181], v0 offset:18624
	ds_read_b128 v[182:185], v0 offset:18656
	s_waitcnt lgkmcnt(14)
	v_mfma_f32_32x32x16_bf16 v[50:65], v[34:37], v[78:81], 0
	v_cmp_ge_u32_e32 vcc, s56, v122
	s_waitcnt lgkmcnt(11)
	v_mfma_f32_32x32x16_bf16 v[34:49], v[38:41], v[78:81], 0
	v_mfma_f32_32x32x16_bf16 v[50:65], v[110:113], v[66:69], v[50:65]
	v_mfma_f32_32x32x16_bf16 v[50:65], v[114:117], v[70:73], v[50:65]
	s_waitcnt lgkmcnt(10)
	v_mfma_f32_32x32x16_bf16 v[34:49], v[136:139], v[66:69], v[34:49]
	v_mfma_f32_32x32x16_bf16 v[50:65], v[132:135], v[74:77], v[50:65]
	s_waitcnt lgkmcnt(9)
	v_mfma_f32_32x32x16_bf16 v[34:49], v[140:143], v[70:73], v[34:49]
	s_waitcnt lgkmcnt(7)
	s_nop 8
	v_fma_f32 v110, v50, s16, -v148
	v_fma_f32 v111, v51, s16, -v149
	v_fma_f32 v50, v52, s16, -v150
	v_fma_f32 v51, v53, s16, -v151
	v_max3_f32 v52, v110, s17, v111
	v_max3_f32 v52, v52, v50, v51
	s_waitcnt lgkmcnt(6)
	v_fma_f32 v114, v54, s16, -v152
	v_fma_f32 v115, v55, s16, -v153
	v_fma_f32 v54, v56, s16, -v154
	v_fma_f32 v55, v57, s16, -v155
	v_max3_f32 v52, v52, v114, v115
	v_mfma_f32_32x32x16_bf16 v[34:49], v[144:147], v[74:77], v[34:49]
	v_max3_f32 v52, v52, v54, v55
	s_waitcnt lgkmcnt(5)
	v_fma_f32 v112, v58, s16, -v156
	v_fma_f32 v113, v59, s16, -v157
	v_fma_f32 v58, v60, s16, -v158
	v_fma_f32 v59, v61, s16, -v159
	v_max3_f32 v52, v52, v112, v113
	v_max3_f32 v52, v52, v58, v59
	s_waitcnt lgkmcnt(4)
	v_fma_f32 v116, v62, s16, -v160
	v_fma_f32 v117, v63, s16, -v161
	v_fma_f32 v56, v64, s16, -v162
	v_fma_f32 v57, v65, s16, -v163
	v_max3_f32 v52, v52, v116, v117
	v_max3_f32 v60, v52, v56, v57
	s_waitcnt lgkmcnt(3)
	v_fma_f32 v62, v34, s16, -v170
	v_fma_f32 v63, v35, s16, -v171
	v_fma_f32 v52, v36, s16, -v172
	v_fma_f32 v53, v37, s16, -v173
	v_max3_f32 v34, v60, v62, v63
	v_max3_f32 v34, v34, v52, v53
	s_waitcnt lgkmcnt(2)
	v_fma_f32 v60, v38, s16, -v174
	v_fma_f32 v61, v39, s16, -v175
	v_fma_f32 v38, v40, s16, -v176
	v_fma_f32 v39, v41, s16, -v177
	v_max3_f32 v34, v34, v60, v61
	v_max3_f32 v34, v34, v38, v39
	s_waitcnt lgkmcnt(1)
	v_fma_f32 v42, v42, s16, -v178
	v_fma_f32 v43, v43, s16, -v179
	v_fma_f32 v36, v44, s16, -v180
	v_fma_f32 v37, v45, s16, -v181
	v_max3_f32 v34, v34, v42, v43
	v_max3_f32 v44, v34, v36, v37
	s_waitcnt lgkmcnt(0)
	v_fma_f32 v40, v46, s16, -v182
	v_fma_f32 v41, v47, s16, -v183
	v_fma_f32 v34, v48, s16, -v184
	v_fma_f32 v35, v49, s16, -v185
	v_max3_f32 v44, v44, v40, v41
	v_max3_f32 v44, v44, v34, v35
	s_and_saveexec_b64 s[36:37], vcc
	s_cbranch_execz .LBB0_552
	v_cmp_lt_i32_e32 vcc, -1, v127
	s_nop 1
	v_cndmask_b32_e32 v110, v167, v110, vcc
	v_cmp_lt_i32_e32 vcc, 0, v127
	s_nop 1
	v_cndmask_b32_e32 v111, v167, v111, vcc
	v_cmp_lt_i32_e32 vcc, 1, v127
	v_max3_f32 v44, v110, s17, v111
	s_nop 0
	v_cndmask_b32_e32 v50, v167, v50, vcc
	v_cmp_lt_i32_e32 vcc, 2, v127
	s_nop 1
	v_cndmask_b32_e32 v51, v167, v51, vcc
	v_cmp_lt_i32_e32 vcc, 7, v127
	v_max3_f32 v44, v44, v50, v51
	s_nop 0
	v_cndmask_b32_e32 v114, v167, v114, vcc
	v_cmp_lt_i32_e32 vcc, 8, v127
	s_nop 1
	v_cndmask_b32_e32 v115, v167, v115, vcc
	v_cmp_lt_i32_e32 vcc, 9, v127
	v_max3_f32 v44, v44, v114, v115
	s_nop 0
	v_cndmask_b32_e32 v54, v167, v54, vcc
	v_cmp_lt_i32_e32 vcc, 10, v127
	s_nop 1
	v_cndmask_b32_e32 v55, v167, v55, vcc
	v_cmp_lt_i32_e32 vcc, 15, v127
	v_max3_f32 v44, v44, v54, v55
	s_nop 0
	v_cndmask_b32_e32 v112, v167, v112, vcc
	v_cmp_lt_i32_e32 vcc, 16, v127
	s_nop 1
	v_cndmask_b32_e32 v113, v167, v113, vcc
	v_cmp_lt_i32_e32 vcc, 17, v127
	v_max3_f32 v44, v44, v112, v113
	s_nop 0
	v_cndmask_b32_e32 v58, v167, v58, vcc
	v_cmp_lt_i32_e32 vcc, 18, v127
	s_nop 1
	v_cndmask_b32_e32 v59, v167, v59, vcc
	v_cmp_lt_i32_e32 vcc, 23, v127
	v_max3_f32 v44, v44, v58, v59
	s_nop 0
	v_cndmask_b32_e32 v116, v167, v116, vcc
	v_cmp_lt_i32_e32 vcc, 24, v127
	s_nop 1
	v_cndmask_b32_e32 v117, v167, v117, vcc
	v_cmp_lt_i32_e32 vcc, 25, v127
	v_max3_f32 v44, v44, v116, v117
	s_nop 0
	v_cndmask_b32_e32 v56, v167, v56, vcc
	v_cmp_lt_i32_e32 vcc, 26, v127
	s_nop 1
	v_cndmask_b32_e32 v57, v167, v57, vcc
	v_cmp_lt_i32_e32 vcc, 31, v127
	v_max3_f32 v44, v44, v56, v57
	s_nop 0
	v_cndmask_b32_e32 v62, v167, v62, vcc
	v_cmp_lt_i32_e32 vcc, 32, v127
	s_nop 1
	v_cndmask_b32_e32 v63, v167, v63, vcc
	v_cmp_lt_i32_e32 vcc, 33, v127
	v_max3_f32 v44, v44, v62, v63
	s_nop 0
	v_cndmask_b32_e32 v52, v167, v52, vcc
	v_cmp_lt_i32_e32 vcc, 34, v127
	s_nop 1
	v_cndmask_b32_e32 v53, v167, v53, vcc
	v_cmp_lt_i32_e32 vcc, 39, v127
	v_max3_f32 v44, v44, v52, v53
	s_nop 0
	v_cndmask_b32_e32 v60, v167, v60, vcc
	v_cmp_lt_i32_e32 vcc, 40, v127
	s_nop 1
	v_cndmask_b32_e32 v61, v167, v61, vcc
	v_cmp_lt_i32_e32 vcc, 41, v127
	v_max3_f32 v44, v44, v60, v61
	s_nop 0
	v_cndmask_b32_e32 v38, v167, v38, vcc
	v_cmp_lt_i32_e32 vcc, 42, v127
	s_nop 1
	v_cndmask_b32_e32 v39, v167, v39, vcc
	v_cmp_lt_i32_e32 vcc, 47, v127
	v_max3_f32 v44, v44, v38, v39
	s_nop 0
	v_cndmask_b32_e32 v42, v167, v42, vcc
	v_cmp_lt_i32_e32 vcc, 48, v127
	s_nop 1
	v_cndmask_b32_e32 v43, v167, v43, vcc
	v_cmp_lt_i32_e32 vcc, 49, v127
	v_max3_f32 v44, v44, v42, v43
	s_nop 0
	v_cndmask_b32_e32 v36, v167, v36, vcc
	v_cmp_lt_i32_e32 vcc, 50, v127
	s_nop 1
	v_cndmask_b32_e32 v37, v167, v37, vcc
	v_cmp_lt_i32_e32 vcc, 55, v127
	v_max3_f32 v44, v44, v36, v37
	s_nop 0
	v_cndmask_b32_e32 v40, v167, v40, vcc
	v_cmp_lt_i32_e32 vcc, 56, v127
	s_nop 1
	v_cndmask_b32_e32 v41, v167, v41, vcc
	v_cmp_lt_i32_e32 vcc, 57, v127
	v_max3_f32 v44, v44, v40, v41
	s_nop 0
	v_cndmask_b32_e32 v34, v167, v34, vcc
	v_cmp_lt_i32_e32 vcc, 58, v127
	s_nop 1
	v_cndmask_b32_e32 v35, v167, v35, vcc
	v_max3_f32 v44, v44, v34, v35
; DI void fox_attn(const Params& P, int bh, int qb, unsigned char* smem, int tt) {
;     ...
;         if (__builtin_amdgcn_ballot_w64(mx + cq - m > 30.f) != 0ull) {
;             mx = fmaxf(mx, shx(mx, 32, lane));
;             const float mn = fmaxf(m, mx + cq);
;             const float alpha = __builtin_amdgcn_exp2f(m - mn);
;             m = mn;
;             l *= alpha;
;             const f32x2v al2 = {alpha, alpha};
; #pragma unroll
;             for (int dt = 0; dt < 2; ++dt)
; #pragma unroll
;                 for (int p2 = 0; p2 < 8; ++p2) {
;                     f32x2v ov = {O[dt][2 * p2], O[dt][2 * p2 + 1]};
;                     ov = ov * al2;
;                     O[dt][2 * p2] = ov.x; O[dt][2 * p2 + 1] = ov.y;
;                 }
;         }
;         {
;             const float sh = cq - m;
;             const f32x2v sh2 = {sh, sh};
;             f32x2v rs2 = {0.f, 0.f};
; #pragma unroll
;             for (int mt = 0; mt < 2; ++mt)
; #pragma unroll
;                 for (int p2 = 0; p2 < 8; ++p2) {
;                     const f32x2v sv = {sacc[mt][2 * p2], sacc[mt][2 * p2 + 1]};
;                     const f32x2v t = sv + sh2;
;                     f32x2v pp; pp.x = __builtin_amdgcn_exp2f(t.x); pp.y = __builtin_amdgcn_exp2f(t.y);
;                     sacc[mt][2 * p2] = pp.x; sacc[mt][2 * p2 + 1] = pp.y;
;                     rs2 = rs2 + pp;
;                 }
;             l += rs2.x + rs2.y;
;     ...
;         {
;             u32x4 vw[2][2][2];
; #pragma unroll
;             for (int mt = 0; mt < 2; ++mt)
; #pragma unroll
;                 for (int s = 0; s < 2; ++s)
; #pragma unroll
;                     for (int dt = 0; dt < 2; ++dt) {
;                         const bf16_t* vp = VTs + (dt * 32 + r) * 72 + mt * 32 + 16 * s + 4 * h2;
;                         const u32x2 lo = *(const u32x2*)vp, hi = *(const u32x2*)(vp + 8);
;                         vw[mt][s][dt].x = lo.x; vw[mt][s][dt].y = lo.y; vw[mt][s][dt].z = hi.x; vw[mt][s][dt].w = hi.y;
;                     }
;             u32x4 pw[2][2];
; #pragma unroll
;             for (int mt = 0; mt < 2; ++mt)
; #pragma unroll
;                 for (int s = 0; s < 2; ++s) {
;                     pw[mt][s].x = pack2(sacc[mt][8 * s + 0], sacc[mt][8 * s + 1]); pw[mt][s].y = pack2(sacc[mt][8 * s + 2], sacc[mt][8 * s + 3]);
.LBB0_552:
	s_or_b64 exec, exec, s[36:37]
	v_add_f32_e32 v45, v121, v44
	v_sub_f32_e32 v45, v45, v128
	s_mov_b32 s35, 0x41f00000
	v_cmp_lt_f32_e32 vcc, s35, v45
	s_cbranch_vccz .LBB0_554
	ds_bpermute_b32 v45, v99, v44
	v_max_f32_e32 v44, v44, v44
	v_max_f32_e32 v46, v128, v128
	s_waitcnt lgkmcnt(0)
	v_max_f32_e32 v45, v45, v45
	v_max_f32_e32 v44, v44, v45
	v_add_f32_e32 v44, v121, v44
	v_max_f32_e32 v45, v46, v44
	v_sub_f32_e32 v44, v128, v45
	v_exp_f32_e32 v44, v44
	v_mov_b32_e32 v128, v45
	v_mul_f32_e32 v32, v32, v44
	v_mul_f32_e32 v33, v33, v44
	v_mul_f32_e32 v30, v30, v44
	v_mul_f32_e32 v31, v31, v44
	v_mul_f32_e32 v28, v28, v44
	v_mul_f32_e32 v29, v29, v44
	v_mul_f32_e32 v26, v26, v44
	v_mul_f32_e32 v27, v27, v44
	v_mul_f32_e32 v24, v24, v44
	v_mul_f32_e32 v25, v25, v44
	v_mul_f32_e32 v22, v22, v44
	v_mul_f32_e32 v23, v23, v44
	v_mul_f32_e32 v20, v20, v44
	v_mul_f32_e32 v21, v21, v44
	v_mul_f32_e32 v18, v18, v44
	v_mul_f32_e32 v19, v19, v44
	v_mul_f32_e32 v16, v16, v44
	v_mul_f32_e32 v17, v17, v44
	v_mul_f32_e32 v14, v14, v44
	v_mul_f32_e32 v15, v15, v44
	v_mul_f32_e32 v12, v12, v44
	v_mul_f32_e32 v13, v13, v44
	v_mul_f32_e32 v10, v10, v44
	v_mul_f32_e32 v11, v11, v44
	v_mul_f32_e32 v8, v8, v44
	v_mul_f32_e32 v9, v9, v44
	v_mul_f32_e32 v6, v6, v44
	v_mul_f32_e32 v7, v7, v44
	v_mul_f32_e32 v4, v4, v44
	v_mul_f32_e32 v5, v5, v44
	v_mul_f32_e32 v2, v2, v44
	v_mul_f32_e32 v3, v3, v44
	v_mul_f32_e32 v120, v120, v44
.LBB0_554:
	v_sub_f32_e32 v132, v121, v128
	v_add_f32_e32 v44, v110, v132
	v_add_f32_e32 v45, v111, v132
	v_lshlrev_b32_e32 v110, 1, v124
	v_add3_u32 v0, v0, v126, v110
	v_add_u32_e32 v129, 0x2000, v0
	v_add_u32_e32 v0, 0x3000, v0
	v_add_f32_e32 v46, v50, v132
	v_add_f32_e32 v47, v51, v132
	v_add_f32_e32 v48, v114, v132
	v_add_f32_e32 v49, v115, v132
	v_add_f32_e32 v50, v54, v132
	v_add_f32_e32 v51, v55, v132
	v_add_f32_e32 v54, v112, v132
	v_add_f32_e32 v55, v113, v132
	v_add_f32_e32 v58, v58, v132
	v_add_f32_e32 v59, v59, v132
	v_add_f32_e32 v64, v116, v132
	v_add_f32_e32 v65, v117, v132
	v_add_f32_e32 v56, v56, v132
	v_add_f32_e32 v57, v57, v132
	v_add_f32_e32 v62, v62, v132
	v_add_f32_e32 v63, v63, v132
	v_add_f32_e32 v52, v52, v132
	v_add_f32_e32 v53, v53, v132
	v_add_f32_e32 v60, v60, v132
	v_add_f32_e32 v61, v61, v132
	v_add_f32_e32 v38, v38, v132
	v_add_f32_e32 v39, v39, v132
	v_add_f32_e32 v42, v42, v132
	v_add_f32_e32 v43, v43, v132
	v_add_f32_e32 v36, v36, v132
	v_add_f32_e32 v37, v37, v132
	v_add_f32_e32 v40, v40, v132
	v_add_f32_e32 v41, v41, v132
	v_add_f32_e32 v34, v34, v132
	v_add_f32_e32 v35, v35, v132
	ds_read2_b64 v[110:113], v129 offset0:128 offset1:130
	ds_read2_b64 v[114:117], v129 offset0:132 offset1:134
	ds_read2_b64 v[132:135], v0 offset0:192 offset1:194
	ds_read2_b64 v[136:139], v0 offset0:196 offset1:198
	ds_read2_b64 v[140:143], v129 offset0:136 offset1:138
	ds_read2_b64 v[144:147], v0 offset0:200 offset1:202
	ds_read2_b64 v[148:151], v129 offset0:140 offset1:142
	ds_read2_b64 v[152:155], v0 offset0:204 offset1:206
	v_exp_f32_e32 v44, v44
	v_exp_f32_e32 v45, v45
	v_exp_f32_e32 v46, v46
	v_exp_f32_e32 v47, v47
	v_exp_f32_e32 v48, v48
	v_exp_f32_e32 v49, v49
	v_exp_f32_e32 v50, v50
	v_exp_f32_e32 v51, v51
	v_exp_f32_e32 v54, v54
	v_exp_f32_e32 v55, v55
	v_exp_f32_e32 v58, v58
	v_exp_f32_e32 v59, v59
	v_exp_f32_e32 v64, v64
	v_exp_f32_e32 v65, v65
	v_exp_f32_e32 v56, v56
	v_exp_f32_e32 v57, v57
	v_exp_f32_e32 v62, v62
	v_exp_f32_e32 v63, v63
	v_exp_f32_e32 v52, v52
	v_exp_f32_e32 v53, v53
	v_exp_f32_e32 v60, v60
	v_exp_f32_e32 v61, v61
	v_exp_f32_e32 v38, v38
	v_exp_f32_e32 v39, v39
	v_exp_f32_e32 v42, v42
	v_exp_f32_e32 v43, v43
	v_exp_f32_e32 v36, v36
	v_exp_f32_e32 v37, v37
	v_exp_f32_e32 v40, v40
	v_exp_f32_e32 v41, v41
	v_exp_f32_e32 v34, v34
	v_exp_f32_e32 v35, v35
	v_cvt_pk_bf16_f32 v156, v44, v45
	v_cvt_pk_bf16_f32 v157, v46, v47
	v_cvt_pk_bf16_f32 v158, v48, v49
	v_cvt_pk_bf16_f32 v159, v50, v51
	v_cvt_pk_bf16_f32 v160, v54, v55
	v_cvt_pk_bf16_f32 v161, v58, v59
	v_cvt_pk_bf16_f32 v162, v64, v65
	v_cvt_pk_bf16_f32 v163, v56, v57
	v_cvt_pk_bf16_f32 v170, v62, v63
	v_cvt_pk_bf16_f32 v171, v52, v53
	v_cvt_pk_bf16_f32 v172, v60, v61
	v_cvt_pk_bf16_f32 v173, v38, v39
	v_cvt_pk_bf16_f32 v174, v42, v43
	v_cvt_pk_bf16_f32 v175, v36, v37
	v_cvt_pk_bf16_f32 v176, v40, v41
	v_cvt_pk_bf16_f32 v177, v34, v35
	s_waitcnt lgkmcnt(7)
	v_mfma_f32_32x32x16_bf16 v[18:33], v[110:113], v[156:159], v[18:33]
	s_waitcnt lgkmcnt(5)
	v_mfma_f32_32x32x16_bf16 v[2:17], v[132:135], v[156:159], v[2:17]
	v_mfma_f32_32x32x16_bf16 v[18:33], v[114:117], v[160:163], v[18:33]
	s_waitcnt lgkmcnt(4)
	v_mfma_f32_32x32x16_bf16 v[2:17], v[136:139], v[160:163], v[2:17]
	s_waitcnt lgkmcnt(3)
	v_mfma_f32_32x32x16_bf16 v[18:33], v[140:143], v[170:173], v[18:33]
	s_waitcnt lgkmcnt(2)
	v_mfma_f32_32x32x16_bf16 v[2:17], v[144:147], v[170:173], v[2:17]
	s_waitcnt lgkmcnt(1)
	v_mfma_f32_32x32x16_bf16 v[18:33], v[148:151], v[174:177], v[18:33]
	s_waitcnt lgkmcnt(0)
	v_mfma_f32_32x32x16_bf16 v[2:17], v[152:155], v[174:177], v[2:17]
	s_and_saveexec_b64 s[36:37], s[2:3]
	s_cbranch_execz .LBB0_545
	s_bitcmp1_b32 s47, 0
	s_cselect_b32 s2, 0x4900, 0
	v_add_u32_e32 v0, s2, v131
	v_add3_u32 v110, v0, v119, v104
	s_waitcnt vmcnt(3)
	ds_write_b128 v110, v[82:85]
	s_waitcnt vmcnt(2)
	ds_write_b128 v110, v[86:89] offset:4608
	s_waitcnt vmcnt(1)
	ds_write_b128 v110, v[90:93] offset:9216
	s_waitcnt vmcnt(0)
	ds_write_b128 v110, v[94:97] offset:13824
	s_and_b64 exec, exec, s[0:1]
	s_cbranch_execz .LBB0_545
	v_mul_f32_e32 v118, 0x3fb8aa3b, v118
	v_lshl_add_u32 v0, v130, 2, v0
	ds_write_b32 v0, v118 offset:18432
	s_branch .LBB0_545
